# MLA phase static unit lists rebalanced: two-tile WGs take 1 uq (not 2 ukv); 64 WGs tile+uq+3ukv; 64 WGs tile+cache ukv+3 ukv; 48 WGs tile+3uq
# baseline (speedup 1.0000x reference)
.LBB0_88:
	s_andn2_b64 vcc, exec, s[2:3]
	s_mov_b64 s[6:7], 0
	s_cbranch_vccnz .LBB0_95
	s_mul_i32 s3, s45, 0x380000
	s_mul_hi_i32 s2, s45, 0x380000
	s_add_u32 s3, s4, s3
	s_addc_u32 s2, s5, s2
	s_add_u32 s8, s3, 0xb00000
	s_addc_u32 s9, s2, 0
	v_writelane_b32 v254, s8, 54
	s_mov_b32 s27, 0
	v_writelane_b32 v254, s9, 55
	s_nop 1
	v_readlane_b32 s8, v254, 23
	s_mul_i32 s9, s8, 3
	s_cmp_lt_u32 s8, 0x50
	s_cbranch_scc1 .Lrb_A
	s_cmp_lt_u32 s8, 0x80
	s_cbranch_scc1 .Lrb_B
	s_cmp_lt_u32 s8, 0x90
	s_cbranch_scc1 .Lrb_M1
	s_cmp_lt_u32 s8, 0xd0
	s_cbranch_scc1 .Lrb_C
	s_add_i32 s73, s8, 32
	s_mov_b32 s14, 1
	s_add_i32 s2, s9, 0xfffffec0
	s_mov_b32 s3, 3
	s_branch .Lrb_noe
.Lrb_M1:
	s_add_i32 s73, s8, 0x60
	s_mov_b32 s14, 1
	s_add_i32 s2, s9, 0xffffff80
	s_mov_b32 s3, 3
	s_branch .Lrb_noe
.Lrb_A:
	s_mov_b32 s73, s8
	s_mov_b32 s14, 1
	s_mov_b32 s2, 0
	s_mov_b32 s3, 0
	s_branch .Lrb_noe
.Lrb_B:
	s_add_i32 s73, s9, 0xffffff60
	s_mov_b32 s14, 3
	s_mov_b32 s2, 0
	s_mov_b32 s3, 0
.Lrb_noe:
	v_writelane_b32 v254, s2, 63
	v_writelane_b32 v254, s3, 62
	s_mov_b32 s2, 0
	v_writelane_b32 v254, s2, 35
	v_writelane_b32 v254, s2, 43
	s_branch .LBB0_1658
.Lrb_C:
	s_mov_b32 s73, 0
	s_mov_b32 s14, 0
	s_add_i32 s2, s9, 0xfffffe90
	s_mov_b32 s3, 3
	v_writelane_b32 v254, s2, 63
	v_writelane_b32 v254, s3, 62
	s_mov_b32 s2, 1
	v_writelane_b32 v254, s2, 35
	s_add_i32 s2, s8, 0xffffff70
	v_writelane_b32 v254, s2, 43
	s_branch .LBB0_1658

.LBB0_1651:
	s_or_saveexec_b64 s[6:7], s[6:7]
	v_mov_b64_e32 v[12:13], s[20:21]
	s_xor_b64 exec, exec, s[6:7]
	s_cbranch_execz .LBB0_1644
	s_mov_b64 s[2:3], s[0:1]
	v_mov_b64_e32 v[10:11], v[46:47]
	v_mov_b64_e32 v[12:13], s[2:3]
	s_branch .LBB0_1644
.LBB0_1658:
	s_nop 0
	v_readlane_b32 s2, v254, 23
	s_mov_b64 s[8:9], 0
	s_mov_b64 s[84:85], -1
	s_mov_b32 s16, s45
	s_mov_b32 s86, s2
	s_andn2_b64 vcc, exec, s[6:7]
	s_cbranch_vccz .LBB0_97
	s_branch .LBB0_98
